# combo + grid barrier: non-leader workgroups issue the acquire invalidate before the generation spin
# speedup vs baseline: 1.0155x; 1.0064x over previous
.LBB0_62:
	s_or_b64 exec, exec, s[18:19]
	v_cvt_f32_u32_e32 v4, v2
	s_waitcnt vmcnt(0)
	v_readfirstlane_b32 s12, v3
	v_sub_u32_e32 v3, 0, v2
	v_rcp_iflag_f32_e32 v4, v4
	v_add_u32_e32 v5, s12, v1
	v_mul_f32_e32 v4, 0x4f7ffffe, v4
	v_cvt_u32_f32_e32 v4, v4
	v_mul_lo_u32 v1, v3, v4
	v_mul_hi_u32 v1, v4, v1
	v_add_u32_e32 v1, v4, v1
	v_mul_hi_u32 v1, v5, v1
	v_mul_lo_u32 v3, v1, v2
	v_sub_u32_e32 v3, v5, v3
	v_add_u32_e32 v4, 1, v1
	v_cmp_ge_u32_e32 vcc, v3, v2
	s_nop 1
	v_cndmask_b32_e32 v1, v1, v4, vcc
	v_sub_u32_e32 v4, v3, v2
	v_cndmask_b32_e32 v3, v3, v4, vcc
	v_add_u32_e32 v4, 1, v1
	v_cmp_ge_u32_e32 vcc, v3, v2
	v_add_u32_e32 v3, 1, v5
	s_nop 0
	v_cndmask_b32_e32 v1, v1, v4, vcc
	v_mul_lo_u32 v4, v2, v1
	v_add_u32_e32 v2, v4, v2
	v_cmp_ne_u32_e32 vcc, v3, v2
	s_and_saveexec_b64 s[12:13], vcc
	s_xor_b64 s[12:13], exec, s[12:13]
	s_cbranch_execz .LBB0_76
	s_waitcnt lgkmcnt(0)
	buffer_inv sc1
	v_mov_b32_e32 v0, 0x2000
	global_load_dword v0, v0, s[4:5] offset:1024 sc1
	s_add_u32 s34, s4, 0x2400
	s_addc_u32 s35, s5, 0
	s_waitcnt vmcnt(0)
	v_cmp_eq_u32_e32 vcc, v0, v1
	s_and_saveexec_b64 s[18:19], vcc
	s_cbranch_execz .LBB0_75
	s_add_u32 s30, s24, 0x22204300
	s_addc_u32 s31, s25, 0
	s_mov_b32 s56, 1
	s_mov_b64 s[36:37], 0
	v_mov_b32_e32 v0, 0
	s_branch .LBB0_66

.LBB0_75:
	s_or_b64 exec, exec, s[18:19]
	s_waitcnt vmcnt(0)

	s_waitcnt vmcnt(0)

.LBB0_160:
	s_or_b64 exec, exec, s[30:31]
	v_cvt_f32_u32_e32 v4, v2
	s_waitcnt vmcnt(0)
	v_readfirstlane_b32 s8, v3
	v_sub_u32_e32 v3, 0, v2
	v_rcp_iflag_f32_e32 v4, v4
	v_add_u32_e32 v5, s8, v1
	v_mul_f32_e32 v4, 0x4f7ffffe, v4
	v_cvt_u32_f32_e32 v4, v4
	v_mul_lo_u32 v1, v3, v4
	v_mul_hi_u32 v1, v4, v1
	v_add_u32_e32 v1, v4, v1
	v_mul_hi_u32 v1, v5, v1
	v_mul_lo_u32 v3, v1, v2
	v_sub_u32_e32 v3, v5, v3
	v_add_u32_e32 v4, 1, v1
	v_cmp_ge_u32_e32 vcc, v3, v2
	s_nop 1
	v_cndmask_b32_e32 v1, v1, v4, vcc
	v_sub_u32_e32 v4, v3, v2
	v_cndmask_b32_e32 v3, v3, v4, vcc
	v_add_u32_e32 v4, 1, v1
	v_cmp_ge_u32_e32 vcc, v3, v2
	v_add_u32_e32 v3, 1, v5
	s_nop 0
	v_cndmask_b32_e32 v1, v1, v4, vcc
	v_mul_lo_u32 v4, v2, v1
	v_add_u32_e32 v2, v4, v2
	v_cmp_ne_u32_e32 vcc, v3, v2
	s_and_saveexec_b64 s[8:9], vcc
	s_xor_b64 s[8:9], exec, s[8:9]
	s_cbranch_execz .LBB0_174
	s_waitcnt lgkmcnt(0)
	buffer_inv sc1
	v_mov_b32_e32 v0, 0x2000
	global_load_dword v0, v0, s[4:5] offset:1024 sc1
	s_add_u32 s36, s4, 0x2400
	s_addc_u32 s37, s5, 0
	s_waitcnt vmcnt(0)
	v_cmp_eq_u32_e32 vcc, v0, v1
	s_and_saveexec_b64 s[30:31], vcc
	s_cbranch_execz .LBB0_173
	s_add_u32 s34, s24, 0x22204300
	s_addc_u32 s35, s25, 0
	s_mov_b32 s54, 1
	s_mov_b64 s[40:41], 0
	v_mov_b32_e32 v0, 0
	s_branch .LBB0_164

.LBB0_173:
	s_or_b64 exec, exec, s[30:31]
	s_waitcnt vmcnt(0)

	s_waitcnt vmcnt(0)

.LBB0_592:
	s_or_b64 exec, exec, s[10:11]
	v_cvt_f32_u32_e32 v4, v2
	s_waitcnt vmcnt(0)
	v_readfirstlane_b32 s8, v3
	v_sub_u32_e32 v3, 0, v2
	v_rcp_iflag_f32_e32 v4, v4
	v_add_u32_e32 v5, s8, v1
	v_mul_f32_e32 v4, 0x4f7ffffe, v4
	v_cvt_u32_f32_e32 v4, v4
	v_mul_lo_u32 v1, v3, v4
	v_mul_hi_u32 v1, v4, v1
	v_add_u32_e32 v1, v4, v1
	v_mul_hi_u32 v1, v5, v1
	v_mul_lo_u32 v3, v1, v2
	v_sub_u32_e32 v3, v5, v3
	v_add_u32_e32 v4, 1, v1
	v_cmp_ge_u32_e32 vcc, v3, v2
	s_nop 1
	v_cndmask_b32_e32 v1, v1, v4, vcc
	v_sub_u32_e32 v4, v3, v2
	v_cndmask_b32_e32 v3, v3, v4, vcc
	v_add_u32_e32 v4, 1, v1
	v_cmp_ge_u32_e32 vcc, v3, v2
	v_add_u32_e32 v3, 1, v5
	s_nop 0
	v_cndmask_b32_e32 v1, v1, v4, vcc
	v_mul_lo_u32 v4, v2, v1
	v_add_u32_e32 v2, v4, v2
	v_cmp_ne_u32_e32 vcc, v3, v2
	s_and_saveexec_b64 s[8:9], vcc
	s_xor_b64 s[8:9], exec, s[8:9]
	s_cbranch_execz .LBB0_606
	s_waitcnt lgkmcnt(0)
	buffer_inv sc1
	v_mov_b32_e32 v0, 0x2000
	global_load_dword v0, v0, s[4:5] offset:1024 sc1
	s_add_u32 s34, s4, 0x2400
	s_addc_u32 s35, s5, 0
	s_waitcnt vmcnt(0)
	v_cmp_eq_u32_e32 vcc, v0, v1
	s_and_saveexec_b64 s[10:11], vcc
	s_cbranch_execz .LBB0_605
	s_add_u32 s30, s24, 0x22204300
	s_addc_u32 s31, s25, 0
	s_mov_b32 s50, 1
	s_mov_b64 s[36:37], 0
	v_mov_b32_e32 v0, 0
	s_branch .LBB0_596

.LBB0_605:
	s_or_b64 exec, exec, s[10:11]
	s_waitcnt vmcnt(0)

	s_waitcnt vmcnt(0)

.LBB0_863:
	s_or_b64 exec, exec, s[10:11]
	v_cvt_f32_u32_e32 v4, v2
	s_waitcnt vmcnt(0)
	v_readfirstlane_b32 s7, v3
	v_sub_u32_e32 v3, 0, v2
	v_rcp_iflag_f32_e32 v4, v4
	v_add_u32_e32 v5, s7, v1
	v_mul_f32_e32 v4, 0x4f7ffffe, v4
	v_cvt_u32_f32_e32 v4, v4
	v_mul_lo_u32 v1, v3, v4
	v_mul_hi_u32 v1, v4, v1
	v_add_u32_e32 v1, v4, v1
	v_mul_hi_u32 v1, v5, v1
	v_mul_lo_u32 v3, v1, v2
	v_sub_u32_e32 v3, v5, v3
	v_add_u32_e32 v4, 1, v1
	v_cmp_ge_u32_e32 vcc, v3, v2
	s_nop 1
	v_cndmask_b32_e32 v1, v1, v4, vcc
	v_sub_u32_e32 v4, v3, v2
	v_cndmask_b32_e32 v3, v3, v4, vcc
	v_add_u32_e32 v4, 1, v1
	v_cmp_ge_u32_e32 vcc, v3, v2
	v_add_u32_e32 v3, 1, v5
	s_nop 0
	v_cndmask_b32_e32 v1, v1, v4, vcc
	v_mul_lo_u32 v4, v2, v1
	v_add_u32_e32 v2, v4, v2
	v_cmp_ne_u32_e32 vcc, v3, v2
	s_and_saveexec_b64 s[8:9], vcc
	s_xor_b64 s[8:9], exec, s[8:9]
	s_cbranch_execz .LBB0_877
	s_waitcnt lgkmcnt(0)
	buffer_inv sc1
	v_mov_b32_e32 v0, 0x2000
	global_load_dword v0, v0, s[4:5] offset:1024 sc1
	s_add_u32 s16, s4, 0x2400
	s_addc_u32 s17, s5, 0
	s_waitcnt vmcnt(0)
	v_cmp_eq_u32_e32 vcc, v0, v1
	s_and_saveexec_b64 s[10:11], vcc
	s_cbranch_execz .LBB0_876
	s_add_u32 s14, s24, 0x22204300
	s_addc_u32 s15, s25, 0
	s_mov_b32 s46, 1
	s_mov_b64 s[30:31], 0
	v_mov_b32_e32 v0, 0
	s_branch .LBB0_867

.LBB0_1159:
	s_or_b64 exec, exec, s[10:11]
	v_cvt_f32_u32_e32 v4, v2
	s_waitcnt vmcnt(0)
	v_readfirstlane_b32 s7, v3
	v_sub_u32_e32 v3, 0, v2
	v_rcp_iflag_f32_e32 v4, v4
	v_add_u32_e32 v5, s7, v1
	v_mul_f32_e32 v4, 0x4f7ffffe, v4
	v_cvt_u32_f32_e32 v4, v4
	v_mul_lo_u32 v1, v3, v4
	v_mul_hi_u32 v1, v4, v1
	v_add_u32_e32 v1, v4, v1
	v_mul_hi_u32 v1, v5, v1
	v_mul_lo_u32 v3, v1, v2
	v_sub_u32_e32 v3, v5, v3
	v_add_u32_e32 v4, 1, v1
	v_cmp_ge_u32_e32 vcc, v3, v2
	s_nop 1
	v_cndmask_b32_e32 v1, v1, v4, vcc
	v_sub_u32_e32 v4, v3, v2
	v_cndmask_b32_e32 v3, v3, v4, vcc
	v_add_u32_e32 v4, 1, v1
	v_cmp_ge_u32_e32 vcc, v3, v2
	v_add_u32_e32 v3, 1, v5
	s_nop 0
	v_cndmask_b32_e32 v1, v1, v4, vcc
	v_mul_lo_u32 v4, v2, v1
	v_add_u32_e32 v2, v4, v2
	v_cmp_ne_u32_e32 vcc, v3, v2
	s_and_saveexec_b64 s[8:9], vcc
	s_xor_b64 s[8:9], exec, s[8:9]
	s_cbranch_execz .LBB0_1173
	s_waitcnt lgkmcnt(0)
	buffer_inv sc1
	v_mov_b32_e32 v0, 0x2000
	global_load_dword v0, v0, s[4:5] offset:1024 sc1
	s_add_u32 s16, s4, 0x2400
	s_addc_u32 s17, s5, 0
	s_waitcnt vmcnt(0)
	v_cmp_eq_u32_e32 vcc, v0, v1
	s_and_saveexec_b64 s[10:11], vcc
	s_cbranch_execz .LBB0_1172
	s_add_u32 s14, s24, 0x22204300
	s_addc_u32 s15, s25, 0
	s_mov_b32 s42, 1
	s_mov_b64 s[20:21], 0
	v_mov_b32_e32 v0, 0
	s_branch .LBB0_1163

.LBB0_1368:
	s_or_b64 exec, exec, s[10:11]
	v_cvt_f32_u32_e32 v4, v2
	s_waitcnt vmcnt(0)
	v_readfirstlane_b32 s7, v3
	v_sub_u32_e32 v3, 0, v2
	v_rcp_iflag_f32_e32 v4, v4
	v_add_u32_e32 v5, s7, v1
	v_mul_f32_e32 v4, 0x4f7ffffe, v4
	v_cvt_u32_f32_e32 v4, v4
	v_mul_lo_u32 v1, v3, v4
	v_mul_hi_u32 v1, v4, v1
	v_add_u32_e32 v1, v4, v1
	v_mul_hi_u32 v1, v5, v1
	v_mul_lo_u32 v3, v1, v2
	v_sub_u32_e32 v3, v5, v3
	v_add_u32_e32 v4, 1, v1
	v_cmp_ge_u32_e32 vcc, v3, v2
	s_nop 1
	v_cndmask_b32_e32 v1, v1, v4, vcc
	v_sub_u32_e32 v4, v3, v2
	v_cndmask_b32_e32 v3, v3, v4, vcc
	v_add_u32_e32 v4, 1, v1
	v_cmp_ge_u32_e32 vcc, v3, v2
	v_add_u32_e32 v3, 1, v5
	s_nop 0
	v_cndmask_b32_e32 v1, v1, v4, vcc
	v_mul_lo_u32 v4, v2, v1
	v_add_u32_e32 v2, v4, v2
	v_cmp_ne_u32_e32 vcc, v3, v2
	s_and_saveexec_b64 s[8:9], vcc
	s_xor_b64 s[8:9], exec, s[8:9]
	s_cbranch_execz .LBB0_1382
	s_waitcnt lgkmcnt(0)
	buffer_inv sc1
	v_mov_b32_e32 v0, 0x2000
	global_load_dword v0, v0, s[4:5] offset:1024 sc1
	s_add_u32 s16, s4, 0x2400
	s_addc_u32 s17, s5, 0
	s_waitcnt vmcnt(0)
	v_cmp_eq_u32_e32 vcc, v0, v1
	s_and_saveexec_b64 s[10:11], vcc
	s_cbranch_execz .LBB0_1381
	s_add_u32 s14, s24, 0x22204300
	s_addc_u32 s15, s25, 0
	s_mov_b32 s7, 1
	s_mov_b64 s[20:21], 0
	v_mov_b32_e32 v0, 0
	s_branch .LBB0_1372

.LBB0_1483:
	s_or_b64 exec, exec, s[6:7]
	v_cvt_f32_u32_e32 v4, v2
	s_waitcnt vmcnt(0)
	v_readfirstlane_b32 s4, v3
	v_sub_u32_e32 v3, 0, v2
	v_rcp_iflag_f32_e32 v4, v4
	v_add_u32_e32 v5, s4, v1
	v_mul_f32_e32 v4, 0x4f7ffffe, v4
	v_cvt_u32_f32_e32 v4, v4
	v_mul_lo_u32 v1, v3, v4
	v_mul_hi_u32 v1, v4, v1
	v_add_u32_e32 v1, v4, v1
	v_mul_hi_u32 v1, v5, v1
	v_mul_lo_u32 v3, v1, v2
	v_sub_u32_e32 v3, v5, v3
	v_add_u32_e32 v4, 1, v1
	v_cmp_ge_u32_e32 vcc, v3, v2
	s_nop 1
	v_cndmask_b32_e32 v1, v1, v4, vcc
	v_sub_u32_e32 v4, v3, v2
	v_cndmask_b32_e32 v3, v3, v4, vcc
	v_add_u32_e32 v4, 1, v1
	v_cmp_ge_u32_e32 vcc, v3, v2
	v_add_u32_e32 v3, 1, v5
	s_nop 0
	v_cndmask_b32_e32 v1, v1, v4, vcc
	v_mul_lo_u32 v4, v2, v1
	v_add_u32_e32 v2, v4, v2
	v_cmp_ne_u32_e32 vcc, v3, v2
	s_and_saveexec_b64 s[4:5], vcc
	s_xor_b64 s[4:5], exec, s[4:5]
	s_cbranch_execz .LBB0_1497
	s_waitcnt lgkmcnt(0)
	buffer_inv sc1
	v_mov_b32_e32 v0, 0x2000
	global_load_dword v0, v0, s[2:3] offset:1024 sc1
	s_add_u32 s10, s2, 0x2400
	s_addc_u32 s11, s3, 0
	s_waitcnt vmcnt(0)
	v_cmp_eq_u32_e32 vcc, v0, v1
	s_and_saveexec_b64 s[6:7], vcc
	s_cbranch_execz .LBB0_1496
	s_add_u32 s8, s24, 0x22204300
	s_addc_u32 s9, s25, 0
	s_mov_b32 s22, 1
	s_mov_b64 s[12:13], 0
	v_mov_b32_e32 v0, 0
	s_branch .LBB0_1487

.LBB0_1496:
	s_or_b64 exec, exec, s[6:7]
	s_waitcnt vmcnt(0)

	s_waitcnt vmcnt(0)
